# GEMM loop: moved As00 LDS-DMA pair from LS2(t) to LS1(t+1), vmcnt 8->6 (rebalance DMA issue)
# speedup vs baseline: 1.0124x; 1.0124x over previous
.LBB0_178:
	s_add_u32 s82, s0, s80
	s_addc_u32 s83, s1, s81
	s_add_u32 s84, s82, 0x460000
	s_addc_u32 s85, s83, 0
	s_cmp_eq_u32 s80, 0x41a0000
	s_cselect_b64 s[86:87], -1, 0
	s_and_b64 s[82:83], s[86:87], exec
	s_cselect_b32 s83, s71, s97
	s_cselect_b32 s82, s73, s79
	s_mov_b32 m0, s9
	s_cselect_b32 s85, s22, s85
	s_cselect_b32 s84, s69, s84
	v_lshl_add_u64 v[246:247], s[82:83], 0, v[194:195]
	s_add_u32 vcc_lo, s82, 0x4000
	global_load_lds_dwordx4 v[246:247], off
	v_lshl_add_u64 v[246:247], s[82:83], 0, v[196:197]
	s_mov_b32 m0, s10
	s_addc_u32 vcc_hi, s83, 0
	global_load_lds_dwordx4 v[246:247], off
	v_lshl_add_u64 v[246:247], vcc, 0, v[194:195]
	s_mov_b32 m0, s11
	s_nop 0
	global_load_lds_dwordx4 v[246:247], off
	v_lshl_add_u64 v[246:247], vcc, 0, v[196:197]
	s_mov_b32 m0, s12
	s_and_b64 vcc, exec, s[48:49]
	global_load_lds_dwordx4 v[246:247], off
	s_mov_b64 s[98:99], s[84:85]
	s_waitcnt vmcnt(6)
	s_waitcnt lgkmcnt(0)
	s_barrier
	s_cbranch_vccnz .LBB0_180
	s_setprio 1
	s_waitcnt lgkmcnt(0)
	v_mfma_f32_16x16x32_bf16 v[54:57], v[146:149], v[174:177], v[54:57]
	v_mfma_f32_16x16x32_bf16 v[62:65], v[154:157], v[174:177], v[62:65]
	v_mfma_f32_16x16x32_bf16 v[38:41], v[146:149], v[170:173], v[38:41]
	v_mfma_f32_16x16x32_bf16 v[46:49], v[154:157], v[170:173], v[46:49]
	v_mfma_f32_16x16x32_bf16 v[22:25], v[146:149], v[166:169], v[22:25]
	v_mfma_f32_16x16x32_bf16 v[30:33], v[154:157], v[166:169], v[30:33]
	v_mfma_f32_16x16x32_bf16 v[10:13], v[146:149], v[162:165], v[10:13]
	v_mfma_f32_16x16x32_bf16 v[14:17], v[154:157], v[162:165], v[14:17]
	v_mfma_f32_16x16x32_bf16 v[54:57], v[150:153], v[190:193], v[54:57]
	v_mfma_f32_16x16x32_bf16 v[62:65], v[158:161], v[190:193], v[62:65]
	v_mfma_f32_16x16x32_bf16 v[38:41], v[150:153], v[186:189], v[38:41]
	v_mfma_f32_16x16x32_bf16 v[46:49], v[158:161], v[186:189], v[46:49]
	v_mfma_f32_16x16x32_bf16 v[22:25], v[150:153], v[182:185], v[22:25]
	v_mfma_f32_16x16x32_bf16 v[30:33], v[158:161], v[182:185], v[30:33]
	v_mfma_f32_16x16x32_bf16 v[10:13], v[150:153], v[178:181], v[10:13]
	v_mfma_f32_16x16x32_bf16 v[14:17], v[158:161], v[178:181], v[14:17]
	s_setprio 0
	s_setprio 1
	v_mfma_f32_16x16x32_bf16 v[58:61], v[130:133], v[174:177], v[58:61]
	v_mfma_f32_16x16x32_bf16 v[50:53], v[138:141], v[174:177], v[50:53]
	v_mfma_f32_16x16x32_bf16 v[42:45], v[130:133], v[170:173], v[42:45]
	v_mfma_f32_16x16x32_bf16 v[34:37], v[138:141], v[170:173], v[34:37]
	v_mfma_f32_16x16x32_bf16 v[26:29], v[130:133], v[166:169], v[26:29]
	v_mfma_f32_16x16x32_bf16 v[18:21], v[138:141], v[166:169], v[18:21]
	v_mfma_f32_16x16x32_bf16 v[6:9], v[130:133], v[162:165], v[6:9]
	v_mfma_f32_16x16x32_bf16 v[2:5], v[138:141], v[162:165], v[2:5]
	v_mfma_f32_16x16x32_bf16 v[58:61], v[134:137], v[190:193], v[58:61]
	v_mfma_f32_16x16x32_bf16 v[50:53], v[142:145], v[190:193], v[50:53]
	v_mfma_f32_16x16x32_bf16 v[42:45], v[134:137], v[186:189], v[42:45]
	v_mfma_f32_16x16x32_bf16 v[34:37], v[142:145], v[186:189], v[34:37]
	v_mfma_f32_16x16x32_bf16 v[26:29], v[134:137], v[182:185], v[26:29]
	v_mfma_f32_16x16x32_bf16 v[18:21], v[142:145], v[182:185], v[18:21]
	v_mfma_f32_16x16x32_bf16 v[6:9], v[134:137], v[178:181], v[6:9]
	v_mfma_f32_16x16x32_bf16 v[2:5], v[142:145], v[178:181], v[2:5]
	s_setprio 0
.LBB0_180:
	s_and_b64 vcc, s[46:47], s[86:87]
	v_cndmask_b32_e64 v131, v233, 0, vcc
	v_cndmask_b32_e32 v130, v232, v198, vcc
	v_lshl_add_u64 v[246:247], s[84:85], 0, v[130:131]
	s_barrier
	s_mov_b32 m0, s8
	v_lshl_add_u64 v[252:253], s[98:99], 0, v[194:195]
	global_load_lds_dwordx4 v[252:253], off
	s_mov_b32 m0, s13
	v_lshl_add_u64 v[252:253], s[98:99], 0, v[196:197]
	global_load_lds_dwordx4 v[252:253], off
	v_add_u32_e32 v130, 0x18000, v243
	v_add_u32_e32 v142, 0x1c000, v243
	ds_read_b128 v[146:149], v130
	ds_read_b128 v[150:153], v130 offset:1024
	ds_read_b128 v[154:157], v130 offset:2048
	ds_read_b128 v[158:161], v130 offset:3072
	ds_read_b128 v[130:133], v142
	ds_read_b128 v[134:137], v142 offset:1024
	ds_read_b128 v[138:141], v142 offset:2048
	ds_read_b128 v[142:145], v142 offset:3072
	s_mov_b32 m0, s14
	v_lshl_add_u64 v[248:249], v[246:247], 0, v[194:195]
	s_waitcnt lgkmcnt(0)
	ds_read_b128 v[174:177], v244 offset:32768
	ds_read_b128 v[190:193], v244 offset:33792
	ds_read_b128 v[170:173], v244 offset:34816
	ds_read_b128 v[186:189], v244 offset:35840
	ds_read_b128 v[166:169], v244 offset:36864
	ds_read_b128 v[182:185], v244 offset:37888
	ds_read_b128 v[162:165], v244 offset:38912
	ds_read_b128 v[178:181], v244 offset:39936
	global_load_lds_dwordx4 v[248:249], off
	v_lshl_add_u64 v[246:247], v[246:247], 0, v[196:197]
	s_mov_b32 m0, s15
	s_nop 0
	global_load_lds_dwordx4 v[246:247], off
	s_waitcnt vmcnt(8)
	s_waitcnt lgkmcnt(0)
	s_barrier
	s_setprio 1
	s_waitcnt lgkmcnt(0)
	v_mfma_f32_16x16x32_bf16 v[118:121], v[146:149], v[174:177], v[118:121]
	v_mfma_f32_16x16x32_bf16 v[126:129], v[154:157], v[174:177], v[126:129]
	v_mfma_f32_16x16x32_bf16 v[102:105], v[146:149], v[170:173], v[102:105]
	v_mfma_f32_16x16x32_bf16 v[110:113], v[154:157], v[170:173], v[110:113]
	v_mfma_f32_16x16x32_bf16 v[86:89], v[146:149], v[166:169], v[86:89]
	v_mfma_f32_16x16x32_bf16 v[94:97], v[154:157], v[166:169], v[94:97]
	v_mfma_f32_16x16x32_bf16 v[70:73], v[146:149], v[162:165], v[70:73]
	v_mfma_f32_16x16x32_bf16 v[78:81], v[154:157], v[162:165], v[78:81]
	v_mfma_f32_16x16x32_bf16 v[118:121], v[150:153], v[190:193], v[118:121]
	v_mfma_f32_16x16x32_bf16 v[126:129], v[158:161], v[190:193], v[126:129]
	v_mfma_f32_16x16x32_bf16 v[102:105], v[150:153], v[186:189], v[102:105]
	v_mfma_f32_16x16x32_bf16 v[110:113], v[158:161], v[186:189], v[110:113]
	v_mfma_f32_16x16x32_bf16 v[86:89], v[150:153], v[182:185], v[86:89]
	v_mfma_f32_16x16x32_bf16 v[94:97], v[158:161], v[182:185], v[94:97]
	v_mfma_f32_16x16x32_bf16 v[70:73], v[150:153], v[178:181], v[70:73]
	v_mfma_f32_16x16x32_bf16 v[78:81], v[158:161], v[178:181], v[78:81]
	s_setprio 0
	s_setprio 1
	v_mfma_f32_16x16x32_bf16 v[122:125], v[130:133], v[174:177], v[122:125]
	v_mfma_f32_16x16x32_bf16 v[114:117], v[138:141], v[174:177], v[114:117]
	v_mfma_f32_16x16x32_bf16 v[106:109], v[130:133], v[170:173], v[106:109]
	v_mfma_f32_16x16x32_bf16 v[98:101], v[138:141], v[170:173], v[98:101]
	v_mfma_f32_16x16x32_bf16 v[90:93], v[130:133], v[166:169], v[90:93]
	v_mfma_f32_16x16x32_bf16 v[82:85], v[138:141], v[166:169], v[82:85]
	v_mfma_f32_16x16x32_bf16 v[74:77], v[130:133], v[162:165], v[74:77]
	v_mfma_f32_16x16x32_bf16 v[66:69], v[138:141], v[162:165], v[66:69]
	v_mfma_f32_16x16x32_bf16 v[122:125], v[134:137], v[190:193], v[122:125]
	v_mfma_f32_16x16x32_bf16 v[114:117], v[142:145], v[190:193], v[114:117]
	v_mfma_f32_16x16x32_bf16 v[106:109], v[134:137], v[186:189], v[106:109]
	v_mfma_f32_16x16x32_bf16 v[98:101], v[142:145], v[186:189], v[98:101]
	v_mfma_f32_16x16x32_bf16 v[90:93], v[134:137], v[182:185], v[90:93]
	v_mfma_f32_16x16x32_bf16 v[82:85], v[142:145], v[182:185], v[82:85]
	v_mfma_f32_16x16x32_bf16 v[74:77], v[134:137], v[178:181], v[74:77]
	v_mfma_f32_16x16x32_bf16 v[66:69], v[142:145], v[178:181], v[66:69]
	s_setprio 0
	s_barrier
	s_and_b64 vcc, exec, s[48:49]
	s_cbranch_vccnz .LBB0_182
	ds_read_b128 v[174:177], v244 offset:49152
	ds_read_b128 v[190:193], v244 offset:50176
	ds_read_b128 v[170:173], v244 offset:51200
	ds_read_b128 v[186:189], v244 offset:52224
	ds_read_b128 v[166:169], v244 offset:53248
	ds_read_b128 v[182:185], v244 offset:54272
	ds_read_b128 v[162:165], v244 offset:55296
	ds_read_b128 v[178:181], v244 offset:56320

.LBB0_561:
	s_add_u32 s60, s56, s58
	s_addc_u32 s61, s57, s59
	s_add_u32 s62, s60, 0x440000
	s_addc_u32 s63, s61, 0
	s_cmp_eq_u32 s58, 0x3fc0000
	s_cselect_b64 s[68:69], -1, 0
	s_and_b64 s[60:61], s[68:69], exec
	s_cselect_b32 s61, s37, s72
	s_cselect_b32 s60, s47, s53
	s_mov_b32 m0, s9
	s_cselect_b32 s63, s1, s63
	s_cselect_b32 s62, s24, s62
	v_lshl_add_u64 v[234:235], s[60:61], 0, v[194:195]
	s_add_u32 s74, s60, 0x4000
	global_load_lds_dwordx4 v[234:235], off
	v_lshl_add_u64 v[234:235], s[60:61], 0, v[196:197]
	s_mov_b32 m0, s10
	s_addc_u32 s75, s61, 0
	global_load_lds_dwordx4 v[234:235], off
	v_lshl_add_u64 v[234:235], s[74:75], 0, v[194:195]
	s_mov_b32 m0, s11
	s_and_b64 vcc, exec, s[42:43]
	global_load_lds_dwordx4 v[234:235], off
	v_lshl_add_u64 v[234:235], s[74:75], 0, v[196:197]
	s_mov_b32 m0, s12
	s_nop 0
	global_load_lds_dwordx4 v[234:235], off
	s_mov_b64 s[98:99], s[62:63]
	s_waitcnt vmcnt(6)
	s_waitcnt lgkmcnt(0)
	s_barrier
	s_cbranch_vccnz .LBB0_563
	s_setprio 1
	s_waitcnt lgkmcnt(0)
	v_mfma_f32_16x16x32_bf16 v[62:65], v[146:149], v[174:177], v[62:65]
	v_mfma_f32_16x16x32_bf16 v[58:61], v[154:157], v[174:177], v[58:61]
	v_mfma_f32_16x16x32_bf16 v[46:49], v[146:149], v[170:173], v[46:49]
	v_mfma_f32_16x16x32_bf16 v[42:45], v[154:157], v[170:173], v[42:45]
	v_mfma_f32_16x16x32_bf16 v[30:33], v[146:149], v[166:169], v[30:33]
	v_mfma_f32_16x16x32_bf16 v[26:29], v[154:157], v[166:169], v[26:29]
	v_mfma_f32_16x16x32_bf16 v[14:17], v[146:149], v[162:165], v[14:17]
	v_mfma_f32_16x16x32_bf16 v[10:13], v[154:157], v[162:165], v[10:13]
	v_mfma_f32_16x16x32_bf16 v[62:65], v[150:153], v[190:193], v[62:65]
	v_mfma_f32_16x16x32_bf16 v[58:61], v[158:161], v[190:193], v[58:61]
	v_mfma_f32_16x16x32_bf16 v[46:49], v[150:153], v[186:189], v[46:49]
	v_mfma_f32_16x16x32_bf16 v[42:45], v[158:161], v[186:189], v[42:45]
	v_mfma_f32_16x16x32_bf16 v[30:33], v[150:153], v[182:185], v[30:33]
	v_mfma_f32_16x16x32_bf16 v[26:29], v[158:161], v[182:185], v[26:29]
	v_mfma_f32_16x16x32_bf16 v[14:17], v[150:153], v[178:181], v[14:17]
	v_mfma_f32_16x16x32_bf16 v[10:13], v[158:161], v[178:181], v[10:13]
	s_setprio 0
	s_setprio 1
	v_mfma_f32_16x16x32_bf16 v[54:57], v[130:133], v[174:177], v[54:57]
	v_mfma_f32_16x16x32_bf16 v[50:53], v[138:141], v[174:177], v[50:53]
	v_mfma_f32_16x16x32_bf16 v[38:41], v[130:133], v[170:173], v[38:41]
	v_mfma_f32_16x16x32_bf16 v[34:37], v[138:141], v[170:173], v[34:37]
	v_mfma_f32_16x16x32_bf16 v[22:25], v[130:133], v[166:169], v[22:25]
	v_mfma_f32_16x16x32_bf16 v[18:21], v[138:141], v[166:169], v[18:21]
	v_mfma_f32_16x16x32_bf16 v[6:9], v[130:133], v[162:165], v[6:9]
	v_mfma_f32_16x16x32_bf16 v[2:5], v[138:141], v[162:165], v[2:5]
	v_mfma_f32_16x16x32_bf16 v[54:57], v[134:137], v[190:193], v[54:57]
	v_mfma_f32_16x16x32_bf16 v[50:53], v[142:145], v[190:193], v[50:53]
	v_mfma_f32_16x16x32_bf16 v[38:41], v[134:137], v[186:189], v[38:41]
	v_mfma_f32_16x16x32_bf16 v[34:37], v[142:145], v[186:189], v[34:37]
	v_mfma_f32_16x16x32_bf16 v[22:25], v[134:137], v[182:185], v[22:25]
	v_mfma_f32_16x16x32_bf16 v[18:21], v[142:145], v[182:185], v[18:21]
	v_mfma_f32_16x16x32_bf16 v[6:9], v[134:137], v[178:181], v[6:9]
	v_mfma_f32_16x16x32_bf16 v[2:5], v[142:145], v[178:181], v[2:5]
	s_setprio 0
.LBB0_563:
	s_and_b64 vcc, s[40:41], s[68:69]
	v_cndmask_b32_e64 v131, v215, 0, vcc
	v_cndmask_b32_e32 v130, v214, v198, vcc
	v_lshl_add_u64 v[234:235], s[62:63], 0, v[130:131]
	s_barrier
	s_mov_b32 m0, s8
	v_lshl_add_u64 v[252:253], s[98:99], 0, v[194:195]
	global_load_lds_dwordx4 v[252:253], off
	s_mov_b32 m0, s13
	v_lshl_add_u64 v[252:253], s[98:99], 0, v[196:197]
	global_load_lds_dwordx4 v[252:253], off
	v_add_u32_e32 v130, 0x18000, v226
	v_add_u32_e32 v142, 0x1c000, v226
	ds_read_b128 v[146:149], v130
	ds_read_b128 v[150:153], v130 offset:1024
	ds_read_b128 v[154:157], v130 offset:2048
	ds_read_b128 v[158:161], v130 offset:3072
	ds_read_b128 v[130:133], v142
	ds_read_b128 v[134:137], v142 offset:1024
	ds_read_b128 v[138:141], v142 offset:2048
	ds_read_b128 v[142:145], v142 offset:3072
	s_mov_b32 m0, s14
	v_lshl_add_u64 v[236:237], v[234:235], 0, v[194:195]
	s_waitcnt lgkmcnt(0)
	ds_read_b128 v[174:177], v229 offset:32768
	ds_read_b128 v[190:193], v229 offset:33792
	ds_read_b128 v[170:173], v229 offset:34816
	ds_read_b128 v[186:189], v229 offset:35840
	ds_read_b128 v[166:169], v229 offset:36864
	ds_read_b128 v[182:185], v229 offset:37888
	ds_read_b128 v[162:165], v229 offset:38912
	ds_read_b128 v[178:181], v229 offset:39936
	global_load_lds_dwordx4 v[236:237], off
	v_lshl_add_u64 v[234:235], v[234:235], 0, v[196:197]
	s_mov_b32 m0, s15
	s_nop 0
	global_load_lds_dwordx4 v[234:235], off
	s_waitcnt vmcnt(8)
	s_waitcnt lgkmcnt(0)
	s_barrier
	s_setprio 1
	s_waitcnt lgkmcnt(0)
	v_mfma_f32_16x16x32_bf16 v[126:129], v[146:149], v[174:177], v[126:129]
	v_mfma_f32_16x16x32_bf16 v[122:125], v[154:157], v[174:177], v[122:125]
	v_mfma_f32_16x16x32_bf16 v[110:113], v[146:149], v[170:173], v[110:113]
	v_mfma_f32_16x16x32_bf16 v[106:109], v[154:157], v[170:173], v[106:109]
	v_mfma_f32_16x16x32_bf16 v[94:97], v[146:149], v[166:169], v[94:97]
	v_mfma_f32_16x16x32_bf16 v[90:93], v[154:157], v[166:169], v[90:93]
	v_mfma_f32_16x16x32_bf16 v[78:81], v[146:149], v[162:165], v[78:81]
	v_mfma_f32_16x16x32_bf16 v[74:77], v[154:157], v[162:165], v[74:77]
	v_mfma_f32_16x16x32_bf16 v[126:129], v[150:153], v[190:193], v[126:129]
	v_mfma_f32_16x16x32_bf16 v[122:125], v[158:161], v[190:193], v[122:125]
	v_mfma_f32_16x16x32_bf16 v[110:113], v[150:153], v[186:189], v[110:113]
	v_mfma_f32_16x16x32_bf16 v[106:109], v[158:161], v[186:189], v[106:109]
	v_mfma_f32_16x16x32_bf16 v[94:97], v[150:153], v[182:185], v[94:97]
	v_mfma_f32_16x16x32_bf16 v[90:93], v[158:161], v[182:185], v[90:93]
	v_mfma_f32_16x16x32_bf16 v[78:81], v[150:153], v[178:181], v[78:81]
	v_mfma_f32_16x16x32_bf16 v[74:77], v[158:161], v[178:181], v[74:77]
	s_setprio 0
	s_setprio 1
	v_mfma_f32_16x16x32_bf16 v[118:121], v[130:133], v[174:177], v[118:121]
	v_mfma_f32_16x16x32_bf16 v[114:117], v[138:141], v[174:177], v[114:117]
	v_mfma_f32_16x16x32_bf16 v[102:105], v[130:133], v[170:173], v[102:105]
	v_mfma_f32_16x16x32_bf16 v[98:101], v[138:141], v[170:173], v[98:101]
	v_mfma_f32_16x16x32_bf16 v[86:89], v[130:133], v[166:169], v[86:89]
	v_mfma_f32_16x16x32_bf16 v[82:85], v[138:141], v[166:169], v[82:85]
	v_mfma_f32_16x16x32_bf16 v[70:73], v[130:133], v[162:165], v[70:73]
	v_mfma_f32_16x16x32_bf16 v[66:69], v[138:141], v[162:165], v[66:69]
	v_mfma_f32_16x16x32_bf16 v[118:121], v[134:137], v[190:193], v[118:121]
	v_mfma_f32_16x16x32_bf16 v[114:117], v[142:145], v[190:193], v[114:117]
	v_mfma_f32_16x16x32_bf16 v[102:105], v[134:137], v[186:189], v[102:105]
	v_mfma_f32_16x16x32_bf16 v[98:101], v[142:145], v[186:189], v[98:101]
	v_mfma_f32_16x16x32_bf16 v[86:89], v[134:137], v[182:185], v[86:89]
	v_mfma_f32_16x16x32_bf16 v[82:85], v[142:145], v[182:185], v[82:85]
	v_mfma_f32_16x16x32_bf16 v[70:73], v[134:137], v[178:181], v[70:73]
	v_mfma_f32_16x16x32_bf16 v[66:69], v[142:145], v[178:181], v[66:69]
	s_setprio 0
	s_barrier
	s_and_b64 vcc, exec, s[42:43]
	s_cbranch_vccnz .LBB0_565
	ds_read_b128 v[174:177], v229 offset:49152
	ds_read_b128 v[190:193], v229 offset:50176
	ds_read_b128 v[170:173], v229 offset:51200
	ds_read_b128 v[186:189], v229 offset:52224
	ds_read_b128 v[166:169], v229 offset:53248
	ds_read_b128 v[182:185], v229 offset:54272
	ds_read_b128 v[162:165], v229 offset:55296
	ds_read_b128 v[178:181], v229 offset:56320

.LBB0_761:
	ds_read_b128 v[130:133], v237
	ds_read_b128 v[134:137], v237 offset:1024
	ds_read_b128 v[138:141], v237 offset:2048
	ds_read_b128 v[142:145], v237 offset:3072
	ds_read_b128 v[146:149], v238
	ds_read_b128 v[150:153], v238 offset:1024
	ds_read_b128 v[154:157], v238 offset:2048
	ds_read_b128 v[158:161], v238 offset:3072
	s_add_u32 s48, s0, 0x21c000
	s_addc_u32 s49, s1, 0
	s_cmp_eq_u32 s67, 28
	s_cselect_b32 s42, s55, s62
	s_cselect_b32 s43, s29, s63
	s_cselect_b32 s52, s45, s48
	s_cselect_b32 s53, s31, s49
	s_add_u32 s50, s42, 0xe0000
	s_addc_u32 s51, s43, 0
	s_add_u32 s48, s52, 0x220000
	s_addc_u32 s49, s53, 0
	v_lshl_add_u64 v[208:209], s[0:1], 0, v[202:203]
	s_add_i32 m0, s9, 0xc000
	ds_read_b128 v[162:165], v239
	ds_read_b128 v[166:169], v239 offset:1024
	ds_read_b128 v[170:173], v239 offset:2048
	ds_read_b128 v[174:177], v239 offset:3072
	ds_read_b128 v[178:181], v239 offset:4096
	ds_read_b128 v[182:185], v239 offset:5120
	ds_read_b128 v[186:189], v239 offset:6144
	ds_read_b128 v[190:193], v239 offset:7168
	global_load_lds_dwordx4 v[208:209], off
	v_lshl_add_u64 v[208:209], s[0:1], 0, v[200:201]
	s_add_i32 m0, s9, 0xe000
	s_nop 0
	global_load_lds_dwordx4 v[208:209], off
	s_waitcnt vmcnt(8)
	s_waitcnt lgkmcnt(0)
	s_barrier
	s_setprio 1
	s_waitcnt lgkmcnt(0)
	v_mfma_f32_16x16x32_bf16 v[126:129], v[130:133], v[162:165], v[126:129]
	v_mfma_f32_16x16x32_bf16 v[122:125], v[138:141], v[162:165], v[122:125]
	v_mfma_f32_16x16x32_bf16 v[118:121], v[130:133], v[170:173], v[118:121]
	v_mfma_f32_16x16x32_bf16 v[114:117], v[138:141], v[170:173], v[114:117]
	v_mfma_f32_16x16x32_bf16 v[110:113], v[130:133], v[178:181], v[110:113]
	v_mfma_f32_16x16x32_bf16 v[106:109], v[138:141], v[178:181], v[106:109]
	v_mfma_f32_16x16x32_bf16 v[102:105], v[130:133], v[186:189], v[102:105]
	v_mfma_f32_16x16x32_bf16 v[98:101], v[138:141], v[186:189], v[98:101]
	v_mfma_f32_16x16x32_bf16 v[126:129], v[134:137], v[166:169], v[126:129]
	v_mfma_f32_16x16x32_bf16 v[122:125], v[142:145], v[166:169], v[122:125]
	v_mfma_f32_16x16x32_bf16 v[118:121], v[134:137], v[174:177], v[118:121]
	v_mfma_f32_16x16x32_bf16 v[114:117], v[142:145], v[174:177], v[114:117]
	v_mfma_f32_16x16x32_bf16 v[110:113], v[134:137], v[182:185], v[110:113]
	v_mfma_f32_16x16x32_bf16 v[106:109], v[142:145], v[182:185], v[106:109]
	v_mfma_f32_16x16x32_bf16 v[102:105], v[134:137], v[190:193], v[102:105]
	v_mfma_f32_16x16x32_bf16 v[98:101], v[142:145], v[190:193], v[98:101]
	s_setprio 0
	s_setprio 1
	v_mfma_f32_16x16x32_bf16 v[62:65], v[146:149], v[162:165], v[62:65]
	s_add_u32 s60, s52, 0x4000
	s_addc_u32 s61, s53, 0
	v_mfma_f32_16x16x32_bf16 v[58:61], v[154:157], v[162:165], v[58:61]
	v_mfma_f32_16x16x32_bf16 v[54:57], v[146:149], v[170:173], v[54:57]
	v_mfma_f32_16x16x32_bf16 v[50:53], v[154:157], v[170:173], v[50:53]
	v_mfma_f32_16x16x32_bf16 v[46:49], v[146:149], v[178:181], v[46:49]
	v_mfma_f32_16x16x32_bf16 v[42:45], v[154:157], v[178:181], v[42:45]
	v_mfma_f32_16x16x32_bf16 v[38:41], v[146:149], v[186:189], v[38:41]
	v_mfma_f32_16x16x32_bf16 v[34:37], v[154:157], v[186:189], v[34:37]
	v_mfma_f32_16x16x32_bf16 v[62:65], v[150:153], v[166:169], v[62:65]
	v_mfma_f32_16x16x32_bf16 v[58:61], v[158:161], v[166:169], v[58:61]
	v_mfma_f32_16x16x32_bf16 v[54:57], v[150:153], v[174:177], v[54:57]
	v_mfma_f32_16x16x32_bf16 v[50:53], v[158:161], v[174:177], v[50:53]
	v_mfma_f32_16x16x32_bf16 v[46:49], v[150:153], v[182:185], v[46:49]
	v_mfma_f32_16x16x32_bf16 v[42:45], v[158:161], v[182:185], v[42:45]
	v_mfma_f32_16x16x32_bf16 v[38:41], v[150:153], v[190:193], v[38:41]
	v_mfma_f32_16x16x32_bf16 v[34:37], v[158:161], v[190:193], v[34:37]
	s_setprio 0
	s_barrier
	s_add_i32 s68, s16, s8
	v_lshl_add_u64 v[208:209], s[42:43], 0, v[194:195]
	s_mov_b32 m0, s68
	ds_read_b128 v[162:165], v239 offset:16384
	ds_read_b128 v[166:169], v239 offset:17408
	ds_read_b128 v[170:173], v239 offset:18432
	ds_read_b128 v[174:177], v239 offset:19456
	ds_read_b128 v[178:181], v239 offset:20480
	ds_read_b128 v[182:185], v239 offset:21504
	ds_read_b128 v[186:189], v239 offset:22528
	ds_read_b128 v[190:193], v239 offset:23552
	global_load_lds_dwordx4 v[208:209], off
	s_add_i32 m0, s68, 0x2000
	s_add_u32 s68, s42, 0x4000
	v_lshl_add_u64 v[208:209], s[42:43], 0, v[196:197]
	s_addc_u32 s69, s43, 0
	s_add_i32 s70, s17, s8
	global_load_lds_dwordx4 v[208:209], off
	v_lshl_add_u64 v[208:209], s[68:69], 0, v[194:195]
	s_mov_b32 m0, s70
	s_nop 0
	global_load_lds_dwordx4 v[208:209], off
	v_lshl_add_u64 v[208:209], s[68:69], 0, v[196:197]
	s_add_i32 m0, s70, 0x2000
	s_nop 0
	global_load_lds_dwordx4 v[208:209], off
	s_mov_b64 s[98:99], s[52:53]
	s_waitcnt vmcnt(6)
	s_waitcnt lgkmcnt(0)
	s_barrier
	s_setprio 1
	s_waitcnt lgkmcnt(0)
	v_mfma_f32_16x16x32_bf16 v[94:97], v[130:133], v[162:165], v[94:97]
	v_mfma_f32_16x16x32_bf16 v[90:93], v[138:141], v[162:165], v[90:93]
	v_mfma_f32_16x16x32_bf16 v[86:89], v[130:133], v[170:173], v[86:89]
	v_mfma_f32_16x16x32_bf16 v[82:85], v[138:141], v[170:173], v[82:85]
	v_mfma_f32_16x16x32_bf16 v[78:81], v[130:133], v[178:181], v[78:81]
	v_mfma_f32_16x16x32_bf16 v[74:77], v[138:141], v[178:181], v[74:77]
	v_mfma_f32_16x16x32_bf16 v[70:73], v[130:133], v[186:189], v[70:73]
	v_mfma_f32_16x16x32_bf16 v[66:69], v[138:141], v[186:189], v[66:69]
	v_mfma_f32_16x16x32_bf16 v[94:97], v[134:137], v[166:169], v[94:97]
	v_mfma_f32_16x16x32_bf16 v[90:93], v[142:145], v[166:169], v[90:93]
	v_mfma_f32_16x16x32_bf16 v[86:89], v[134:137], v[174:177], v[86:89]
	v_mfma_f32_16x16x32_bf16 v[82:85], v[142:145], v[174:177], v[82:85]
	v_mfma_f32_16x16x32_bf16 v[78:81], v[134:137], v[182:185], v[78:81]
	v_mfma_f32_16x16x32_bf16 v[74:77], v[142:145], v[182:185], v[74:77]
	v_mfma_f32_16x16x32_bf16 v[70:73], v[134:137], v[190:193], v[70:73]
	v_mfma_f32_16x16x32_bf16 v[66:69], v[142:145], v[190:193], v[66:69]
	s_setprio 0
	s_setprio 1
	v_mfma_f32_16x16x32_bf16 v[30:33], v[146:149], v[162:165], v[30:33]
	v_mfma_f32_16x16x32_bf16 v[26:29], v[154:157], v[162:165], v[26:29]
	v_mfma_f32_16x16x32_bf16 v[22:25], v[146:149], v[170:173], v[22:25]
	v_mfma_f32_16x16x32_bf16 v[18:21], v[154:157], v[170:173], v[18:21]
	v_mfma_f32_16x16x32_bf16 v[14:17], v[146:149], v[178:181], v[14:17]
	v_mfma_f32_16x16x32_bf16 v[10:13], v[154:157], v[178:181], v[10:13]
	v_mfma_f32_16x16x32_bf16 v[6:9], v[146:149], v[186:189], v[6:9]
	v_mfma_f32_16x16x32_bf16 v[2:5], v[154:157], v[186:189], v[2:5]
	v_mfma_f32_16x16x32_bf16 v[30:33], v[150:153], v[166:169], v[30:33]
	v_mfma_f32_16x16x32_bf16 v[26:29], v[158:161], v[166:169], v[26:29]
	v_mfma_f32_16x16x32_bf16 v[22:25], v[150:153], v[174:177], v[22:25]
	v_mfma_f32_16x16x32_bf16 v[18:21], v[158:161], v[174:177], v[18:21]
	v_mfma_f32_16x16x32_bf16 v[14:17], v[150:153], v[182:185], v[14:17]
	v_mfma_f32_16x16x32_bf16 v[10:13], v[158:161], v[182:185], v[10:13]
	v_mfma_f32_16x16x32_bf16 v[6:9], v[150:153], v[190:193], v[6:9]
	v_mfma_f32_16x16x32_bf16 v[2:5], v[158:161], v[190:193], v[2:5]
	s_setprio 0
	s_barrier
	s_mov_b32 m0, s9
	v_lshl_add_u64 v[252:253], s[98:99], 0, v[194:195]
	global_load_lds_dwordx4 v[252:253], off
	s_mov_b32 m0, s10
	v_lshl_add_u64 v[252:253], s[98:99], 0, v[196:197]
	global_load_lds_dwordx4 v[252:253], off
	s_add_i32 s52, 0, 0x18000
	s_add_i32 s53, 0, 0x1c000
	v_add_u32_e32 v142, s52, v228
	v_add_u32_e32 v158, s53, v228
	ds_read_b128 v[130:133], v142
	ds_read_b128 v[134:137], v142 offset:1024
	ds_read_b128 v[138:141], v142 offset:2048
	ds_read_b128 v[142:145], v142 offset:3072
	ds_read_b128 v[146:149], v158
	ds_read_b128 v[150:153], v158 offset:1024
	ds_read_b128 v[154:157], v158 offset:2048
	ds_read_b128 v[158:161], v158 offset:3072
	s_mov_b32 m0, s11
	v_lshl_add_u64 v[208:209], s[60:61], 0, v[194:195]
	ds_read_b128 v[162:165], v239 offset:32768
	ds_read_b128 v[166:169], v239 offset:33792
	ds_read_b128 v[170:173], v239 offset:34816
	ds_read_b128 v[174:177], v239 offset:35840
	ds_read_b128 v[178:181], v239 offset:36864
	ds_read_b128 v[182:185], v239 offset:37888
	ds_read_b128 v[186:189], v239 offset:38912
	ds_read_b128 v[190:193], v239 offset:39936
	global_load_lds_dwordx4 v[208:209], off
	v_lshl_add_u64 v[208:209], s[60:61], 0, v[196:197]
	s_mov_b32 m0, s12
	s_nop 0
	global_load_lds_dwordx4 v[208:209], off
	s_waitcnt vmcnt(8)
	s_waitcnt lgkmcnt(0)
	s_barrier
	s_setprio 1
	s_waitcnt lgkmcnt(0)
	v_mfma_f32_16x16x32_bf16 v[126:129], v[130:133], v[162:165], v[126:129]
	v_mfma_f32_16x16x32_bf16 v[122:125], v[138:141], v[162:165], v[122:125]
	v_mfma_f32_16x16x32_bf16 v[118:121], v[130:133], v[170:173], v[118:121]
	v_mfma_f32_16x16x32_bf16 v[114:117], v[138:141], v[170:173], v[114:117]
	v_mfma_f32_16x16x32_bf16 v[110:113], v[130:133], v[178:181], v[110:113]
	v_mfma_f32_16x16x32_bf16 v[106:109], v[138:141], v[178:181], v[106:109]
	v_mfma_f32_16x16x32_bf16 v[102:105], v[130:133], v[186:189], v[102:105]
	v_mfma_f32_16x16x32_bf16 v[98:101], v[138:141], v[186:189], v[98:101]
	v_mfma_f32_16x16x32_bf16 v[126:129], v[134:137], v[166:169], v[126:129]
	v_mfma_f32_16x16x32_bf16 v[122:125], v[142:145], v[166:169], v[122:125]
	v_mfma_f32_16x16x32_bf16 v[118:121], v[134:137], v[174:177], v[118:121]
	v_mfma_f32_16x16x32_bf16 v[114:117], v[142:145], v[174:177], v[114:117]
	v_mfma_f32_16x16x32_bf16 v[110:113], v[134:137], v[182:185], v[110:113]
	v_mfma_f32_16x16x32_bf16 v[106:109], v[142:145], v[182:185], v[106:109]
	v_mfma_f32_16x16x32_bf16 v[102:105], v[134:137], v[190:193], v[102:105]
	v_mfma_f32_16x16x32_bf16 v[98:101], v[142:145], v[190:193], v[98:101]
	s_setprio 0
	s_setprio 1
	v_mfma_f32_16x16x32_bf16 v[62:65], v[146:149], v[162:165], v[62:65]
	v_mfma_f32_16x16x32_bf16 v[58:61], v[154:157], v[162:165], v[58:61]
	v_mfma_f32_16x16x32_bf16 v[54:57], v[146:149], v[170:173], v[54:57]
	v_mfma_f32_16x16x32_bf16 v[50:53], v[154:157], v[170:173], v[50:53]
	v_mfma_f32_16x16x32_bf16 v[46:49], v[146:149], v[178:181], v[46:49]
	v_mfma_f32_16x16x32_bf16 v[42:45], v[154:157], v[178:181], v[42:45]
	v_mfma_f32_16x16x32_bf16 v[38:41], v[146:149], v[186:189], v[38:41]
	v_mfma_f32_16x16x32_bf16 v[34:37], v[154:157], v[186:189], v[34:37]
	v_mfma_f32_16x16x32_bf16 v[62:65], v[150:153], v[166:169], v[62:65]
	v_mfma_f32_16x16x32_bf16 v[58:61], v[158:161], v[166:169], v[58:61]
	v_mfma_f32_16x16x32_bf16 v[54:57], v[150:153], v[174:177], v[54:57]
	v_mfma_f32_16x16x32_bf16 v[50:53], v[158:161], v[174:177], v[50:53]
	v_mfma_f32_16x16x32_bf16 v[46:49], v[150:153], v[182:185], v[46:49]
	v_mfma_f32_16x16x32_bf16 v[42:45], v[158:161], v[182:185], v[42:45]
	v_mfma_f32_16x16x32_bf16 v[38:41], v[150:153], v[190:193], v[38:41]
	v_mfma_f32_16x16x32_bf16 v[34:37], v[158:161], v[190:193], v[34:37]
	s_setprio 0
	s_barrier
	s_add_i32 s52, s52, s8
	v_lshl_add_u64 v[208:209], s[50:51], 0, v[194:195]
	s_mov_b32 m0, s52
	ds_read_b128 v[162:165], v239 offset:49152
	ds_read_b128 v[166:169], v239 offset:50176
	ds_read_b128 v[170:173], v239 offset:51200
	ds_read_b128 v[174:177], v239 offset:52224
	ds_read_b128 v[178:181], v239 offset:53248
	ds_read_b128 v[182:185], v239 offset:54272
	ds_read_b128 v[186:189], v239 offset:55296
	ds_read_b128 v[190:193], v239 offset:56320
	global_load_lds_dwordx4 v[208:209], off
	s_add_i32 m0, s52, 0x2000
	s_add_u32 s42, s42, 0xe4000
	v_lshl_add_u64 v[208:209], s[50:51], 0, v[196:197]
	s_addc_u32 s43, s43, 0
	s_add_i32 s50, s53, s8
	global_load_lds_dwordx4 v[208:209], off
	v_lshl_add_u64 v[208:209], s[42:43], 0, v[194:195]
	s_mov_b32 m0, s50
	s_nop 0
	global_load_lds_dwordx4 v[208:209], off
	v_lshl_add_u64 v[208:209], s[42:43], 0, v[196:197]
	s_add_i32 m0, s50, 0x2000
	s_nop 0
	global_load_lds_dwordx4 v[208:209], off
	v_lshl_add_u64 v[208:209], s[48:49], 0, v[194:195]
	s_mov_b32 m0, s14
	s_nop 0
	global_load_lds_dwordx4 v[208:209], off
	v_lshl_add_u64 v[208:209], s[48:49], 0, v[196:197]
	s_mov_b32 m0, s15
	s_nop 0
	global_load_lds_dwordx4 v[208:209], off
	s_waitcnt vmcnt(8)
	s_waitcnt lgkmcnt(0)
	s_barrier
	s_setprio 1
	s_waitcnt lgkmcnt(0)
	v_mfma_f32_16x16x32_bf16 v[94:97], v[130:133], v[162:165], v[94:97]
	v_mfma_f32_16x16x32_bf16 v[90:93], v[138:141], v[162:165], v[90:93]
	v_mfma_f32_16x16x32_bf16 v[86:89], v[130:133], v[170:173], v[86:89]
	v_mfma_f32_16x16x32_bf16 v[82:85], v[138:141], v[170:173], v[82:85]
	v_mfma_f32_16x16x32_bf16 v[78:81], v[130:133], v[178:181], v[78:81]
	v_mfma_f32_16x16x32_bf16 v[74:77], v[138:141], v[178:181], v[74:77]
	v_mfma_f32_16x16x32_bf16 v[70:73], v[130:133], v[186:189], v[70:73]
	v_mfma_f32_16x16x32_bf16 v[66:69], v[138:141], v[186:189], v[66:69]
	v_mfma_f32_16x16x32_bf16 v[94:97], v[134:137], v[166:169], v[94:97]
	v_mfma_f32_16x16x32_bf16 v[90:93], v[142:145], v[166:169], v[90:93]
	v_mfma_f32_16x16x32_bf16 v[86:89], v[134:137], v[174:177], v[86:89]
	v_mfma_f32_16x16x32_bf16 v[82:85], v[142:145], v[174:177], v[82:85]
	v_mfma_f32_16x16x32_bf16 v[78:81], v[134:137], v[182:185], v[78:81]
	v_mfma_f32_16x16x32_bf16 v[74:77], v[142:145], v[182:185], v[74:77]
	v_mfma_f32_16x16x32_bf16 v[70:73], v[134:137], v[190:193], v[70:73]
	v_mfma_f32_16x16x32_bf16 v[66:69], v[142:145], v[190:193], v[66:69]
	s_setprio 0
	s_setprio 1
	v_mfma_f32_16x16x32_bf16 v[30:33], v[146:149], v[162:165], v[30:33]
	v_mfma_f32_16x16x32_bf16 v[26:29], v[154:157], v[162:165], v[26:29]
	v_mfma_f32_16x16x32_bf16 v[22:25], v[146:149], v[170:173], v[22:25]
	v_mfma_f32_16x16x32_bf16 v[18:21], v[154:157], v[170:173], v[18:21]
	v_mfma_f32_16x16x32_bf16 v[14:17], v[146:149], v[178:181], v[14:17]
	v_mfma_f32_16x16x32_bf16 v[10:13], v[154:157], v[178:181], v[10:13]
	v_mfma_f32_16x16x32_bf16 v[6:9], v[146:149], v[186:189], v[6:9]
	v_mfma_f32_16x16x32_bf16 v[2:5], v[154:157], v[186:189], v[2:5]
	v_mfma_f32_16x16x32_bf16 v[30:33], v[150:153], v[166:169], v[30:33]
	v_mfma_f32_16x16x32_bf16 v[26:29], v[158:161], v[166:169], v[26:29]
	v_mfma_f32_16x16x32_bf16 v[22:25], v[150:153], v[174:177], v[22:25]
	v_mfma_f32_16x16x32_bf16 v[18:21], v[158:161], v[174:177], v[18:21]
	v_mfma_f32_16x16x32_bf16 v[14:17], v[150:153], v[182:185], v[14:17]
	v_mfma_f32_16x16x32_bf16 v[10:13], v[158:161], v[182:185], v[10:13]
	v_mfma_f32_16x16x32_bf16 v[6:9], v[150:153], v[190:193], v[6:9]
	v_mfma_f32_16x16x32_bf16 v[2:5], v[158:161], v[190:193], v[2:5]
	s_setprio 0
	s_barrier
	s_add_i32 s67, s67, 2
	s_add_u32 s62, s62, 0x1c0000
	s_addc_u32 s63, s63, 0
	s_add_u32 s0, s0, 0x440000
	s_addc_u32 s1, s1, 0
	s_cmp_gt_u32 s67, 29
	s_cbranch_scc0 .LBB0_761
	s_and_b64 vcc, exec, s[26:27]
	s_cbranch_vccz .LBB0_764
	s_barrier

.LBB0_905:
	s_add_u32 s68, s0, s62
	s_addc_u32 s69, s1, s63
	s_add_u32 s70, s68, 0x440000
	s_addc_u32 s71, s69, 0
	s_cmp_eq_u32 s62, 0x3fc0000
	s_cselect_b64 s[72:73], -1, 0
	s_and_b64 s[68:69], s[72:73], exec
	s_cselect_b32 s69, s37, s77
	s_cselect_b32 s68, s75, s76
	s_mov_b32 m0, s9
	s_cselect_b32 s71, s35, s71
	s_cselect_b32 s70, s74, s70
	v_lshl_add_u64 v[234:235], s[68:69], 0, v[194:195]
	s_add_u32 s80, s68, 0x4000
	global_load_lds_dwordx4 v[234:235], off
	v_lshl_add_u64 v[234:235], s[68:69], 0, v[196:197]
	s_mov_b32 m0, s10
	s_addc_u32 s81, s69, 0
	global_load_lds_dwordx4 v[234:235], off
	v_lshl_add_u64 v[234:235], s[80:81], 0, v[194:195]
	s_mov_b32 m0, s11
	s_and_b64 vcc, exec, s[42:43]
	global_load_lds_dwordx4 v[234:235], off
	v_lshl_add_u64 v[234:235], s[80:81], 0, v[196:197]
	s_mov_b32 m0, s12
	s_nop 0
	global_load_lds_dwordx4 v[234:235], off
	s_mov_b64 s[98:99], s[70:71]
	s_waitcnt vmcnt(6)
	s_waitcnt lgkmcnt(0)
	s_barrier
	s_cbranch_vccnz .LBB0_907
	s_setprio 1
	s_waitcnt lgkmcnt(0)
	v_mfma_f32_16x16x32_bf16 v[62:65], v[146:149], v[174:177], v[62:65]
	v_mfma_f32_16x16x32_bf16 v[58:61], v[154:157], v[174:177], v[58:61]
	v_mfma_f32_16x16x32_bf16 v[54:57], v[146:149], v[170:173], v[54:57]
	v_mfma_f32_16x16x32_bf16 v[50:53], v[154:157], v[170:173], v[50:53]
	v_mfma_f32_16x16x32_bf16 v[46:49], v[146:149], v[166:169], v[46:49]
	v_mfma_f32_16x16x32_bf16 v[42:45], v[154:157], v[166:169], v[42:45]
	v_mfma_f32_16x16x32_bf16 v[38:41], v[146:149], v[162:165], v[38:41]
	v_mfma_f32_16x16x32_bf16 v[34:37], v[154:157], v[162:165], v[34:37]
	v_mfma_f32_16x16x32_bf16 v[62:65], v[150:153], v[190:193], v[62:65]
	v_mfma_f32_16x16x32_bf16 v[58:61], v[158:161], v[190:193], v[58:61]
	v_mfma_f32_16x16x32_bf16 v[54:57], v[150:153], v[186:189], v[54:57]
	v_mfma_f32_16x16x32_bf16 v[50:53], v[158:161], v[186:189], v[50:53]
	v_mfma_f32_16x16x32_bf16 v[46:49], v[150:153], v[182:185], v[46:49]
	v_mfma_f32_16x16x32_bf16 v[42:45], v[158:161], v[182:185], v[42:45]
	v_mfma_f32_16x16x32_bf16 v[38:41], v[150:153], v[178:181], v[38:41]
	v_mfma_f32_16x16x32_bf16 v[34:37], v[158:161], v[178:181], v[34:37]
	s_setprio 0
	s_setprio 1
	v_mfma_f32_16x16x32_bf16 v[30:33], v[130:133], v[174:177], v[30:33]
	v_mfma_f32_16x16x32_bf16 v[26:29], v[138:141], v[174:177], v[26:29]
	v_mfma_f32_16x16x32_bf16 v[22:25], v[130:133], v[170:173], v[22:25]
	v_mfma_f32_16x16x32_bf16 v[18:21], v[138:141], v[170:173], v[18:21]
	v_mfma_f32_16x16x32_bf16 v[14:17], v[130:133], v[166:169], v[14:17]
	v_mfma_f32_16x16x32_bf16 v[10:13], v[138:141], v[166:169], v[10:13]
	v_mfma_f32_16x16x32_bf16 v[6:9], v[130:133], v[162:165], v[6:9]
	v_mfma_f32_16x16x32_bf16 v[2:5], v[138:141], v[162:165], v[2:5]
	v_mfma_f32_16x16x32_bf16 v[30:33], v[134:137], v[190:193], v[30:33]
	v_mfma_f32_16x16x32_bf16 v[26:29], v[142:145], v[190:193], v[26:29]
	v_mfma_f32_16x16x32_bf16 v[22:25], v[134:137], v[186:189], v[22:25]
	v_mfma_f32_16x16x32_bf16 v[18:21], v[142:145], v[186:189], v[18:21]
	v_mfma_f32_16x16x32_bf16 v[14:17], v[134:137], v[182:185], v[14:17]
	v_mfma_f32_16x16x32_bf16 v[10:13], v[142:145], v[182:185], v[10:13]
	v_mfma_f32_16x16x32_bf16 v[6:9], v[134:137], v[178:181], v[6:9]
	v_mfma_f32_16x16x32_bf16 v[2:5], v[142:145], v[178:181], v[2:5]
	s_setprio 0
.LBB0_907:
	s_and_b64 vcc, s[40:41], s[72:73]
	v_cndmask_b32_e64 v131, v209, 0, vcc
	v_cndmask_b32_e32 v130, v208, v198, vcc
	v_lshl_add_u64 v[234:235], s[70:71], 0, v[130:131]
	s_barrier
	s_mov_b32 m0, s8
	v_lshl_add_u64 v[252:253], s[98:99], 0, v[194:195]
	global_load_lds_dwordx4 v[252:253], off
	s_mov_b32 m0, s13
	v_lshl_add_u64 v[252:253], s[98:99], 0, v[196:197]
	global_load_lds_dwordx4 v[252:253], off
	v_add_u32_e32 v130, 0x18000, v224
	v_add_u32_e32 v142, 0x1c000, v224
	ds_read_b128 v[146:149], v130
	ds_read_b128 v[150:153], v130 offset:1024
	ds_read_b128 v[154:157], v130 offset:2048
	ds_read_b128 v[158:161], v130 offset:3072
	ds_read_b128 v[130:133], v142
	ds_read_b128 v[134:137], v142 offset:1024
	ds_read_b128 v[138:141], v142 offset:2048
	ds_read_b128 v[142:145], v142 offset:3072
	s_mov_b32 m0, s14
	v_lshl_add_u64 v[236:237], v[234:235], 0, v[194:195]
	s_waitcnt lgkmcnt(0)
	ds_read_b128 v[174:177], v228 offset:32768
	ds_read_b128 v[190:193], v228 offset:33792
	ds_read_b128 v[170:173], v228 offset:34816
	ds_read_b128 v[186:189], v228 offset:35840
	ds_read_b128 v[166:169], v228 offset:36864
	ds_read_b128 v[182:185], v228 offset:37888
	ds_read_b128 v[162:165], v228 offset:38912
	ds_read_b128 v[178:181], v228 offset:39936
	global_load_lds_dwordx4 v[236:237], off
	v_lshl_add_u64 v[234:235], v[234:235], 0, v[196:197]
	s_mov_b32 m0, s15
	s_nop 0
	global_load_lds_dwordx4 v[234:235], off
	s_waitcnt vmcnt(8)
	s_waitcnt lgkmcnt(0)
	s_barrier
	s_setprio 1
	s_waitcnt lgkmcnt(0)
	v_mfma_f32_16x16x32_bf16 v[126:129], v[146:149], v[174:177], v[126:129]
	v_mfma_f32_16x16x32_bf16 v[122:125], v[154:157], v[174:177], v[122:125]
	v_mfma_f32_16x16x32_bf16 v[118:121], v[146:149], v[170:173], v[118:121]
	v_mfma_f32_16x16x32_bf16 v[114:117], v[154:157], v[170:173], v[114:117]
	v_mfma_f32_16x16x32_bf16 v[110:113], v[146:149], v[166:169], v[110:113]
	v_mfma_f32_16x16x32_bf16 v[106:109], v[154:157], v[166:169], v[106:109]
	v_mfma_f32_16x16x32_bf16 v[102:105], v[146:149], v[162:165], v[102:105]
	v_mfma_f32_16x16x32_bf16 v[98:101], v[154:157], v[162:165], v[98:101]
	v_mfma_f32_16x16x32_bf16 v[126:129], v[150:153], v[190:193], v[126:129]
	v_mfma_f32_16x16x32_bf16 v[122:125], v[158:161], v[190:193], v[122:125]
	v_mfma_f32_16x16x32_bf16 v[118:121], v[150:153], v[186:189], v[118:121]
	v_mfma_f32_16x16x32_bf16 v[114:117], v[158:161], v[186:189], v[114:117]
	v_mfma_f32_16x16x32_bf16 v[110:113], v[150:153], v[182:185], v[110:113]
	v_mfma_f32_16x16x32_bf16 v[106:109], v[158:161], v[182:185], v[106:109]
	v_mfma_f32_16x16x32_bf16 v[102:105], v[150:153], v[178:181], v[102:105]
	v_mfma_f32_16x16x32_bf16 v[98:101], v[158:161], v[178:181], v[98:101]
	s_setprio 0
	s_setprio 1
	v_mfma_f32_16x16x32_bf16 v[94:97], v[130:133], v[174:177], v[94:97]
	v_mfma_f32_16x16x32_bf16 v[90:93], v[138:141], v[174:177], v[90:93]
	v_mfma_f32_16x16x32_bf16 v[86:89], v[130:133], v[170:173], v[86:89]
	v_mfma_f32_16x16x32_bf16 v[82:85], v[138:141], v[170:173], v[82:85]
	v_mfma_f32_16x16x32_bf16 v[78:81], v[130:133], v[166:169], v[78:81]
	v_mfma_f32_16x16x32_bf16 v[74:77], v[138:141], v[166:169], v[74:77]
	v_mfma_f32_16x16x32_bf16 v[70:73], v[130:133], v[162:165], v[70:73]
	v_mfma_f32_16x16x32_bf16 v[66:69], v[138:141], v[162:165], v[66:69]
	v_mfma_f32_16x16x32_bf16 v[94:97], v[134:137], v[190:193], v[94:97]
	v_mfma_f32_16x16x32_bf16 v[90:93], v[142:145], v[190:193], v[90:93]
	v_mfma_f32_16x16x32_bf16 v[86:89], v[134:137], v[186:189], v[86:89]
	v_mfma_f32_16x16x32_bf16 v[82:85], v[142:145], v[186:189], v[82:85]
	v_mfma_f32_16x16x32_bf16 v[78:81], v[134:137], v[182:185], v[78:81]
	v_mfma_f32_16x16x32_bf16 v[74:77], v[142:145], v[182:185], v[74:77]
	v_mfma_f32_16x16x32_bf16 v[70:73], v[134:137], v[178:181], v[70:73]
	v_mfma_f32_16x16x32_bf16 v[66:69], v[142:145], v[178:181], v[66:69]
	s_setprio 0
	s_barrier
	s_and_b64 vcc, exec, s[42:43]
	s_cbranch_vccnz .LBB0_909
	ds_read_b128 v[174:177], v228 offset:49152
	ds_read_b128 v[190:193], v228 offset:50176
	ds_read_b128 v[170:173], v228 offset:51200
	ds_read_b128 v[186:189], v228 offset:52224
	ds_read_b128 v[166:169], v228 offset:53248
	ds_read_b128 v[182:185], v228 offset:54272
	ds_read_b128 v[162:165], v228 offset:55296
	ds_read_b128 v[178:181], v228 offset:56320

.LBB0_1291:
	s_add_u32 s52, s36, s48
	s_addc_u32 s53, s37, s49
	s_add_u32 s56, s52, 0x440000
	s_addc_u32 s57, s53, 0
	s_cmp_eq_u32 s48, 0x3fc0000
	s_cselect_b64 s[58:59], -1, 0
	s_and_b64 s[52:53], s[58:59], exec
	s_cselect_b32 s53, s31, s63
	s_cselect_b32 s52, s61, s62
	s_mov_b32 m0, s9
	s_cselect_b32 s57, s19, s57
	s_cselect_b32 s56, s29, s56
	v_lshl_add_u64 v[234:235], s[52:53], 0, v[194:195]
	s_add_u32 s68, s52, 0x4000
	global_load_lds_dwordx4 v[234:235], off
	v_lshl_add_u64 v[234:235], s[52:53], 0, v[196:197]
	s_mov_b32 m0, s10
	s_addc_u32 s69, s53, 0
	global_load_lds_dwordx4 v[234:235], off
	v_lshl_add_u64 v[234:235], s[68:69], 0, v[194:195]
	s_mov_b32 m0, s11
	s_and_b64 vcc, exec, s[42:43]
	global_load_lds_dwordx4 v[234:235], off
	v_lshl_add_u64 v[234:235], s[68:69], 0, v[196:197]
	s_mov_b32 m0, s12
	s_nop 0
	global_load_lds_dwordx4 v[234:235], off
	s_mov_b64 s[98:99], s[56:57]
	s_waitcnt vmcnt(6)
	s_waitcnt lgkmcnt(0)
	s_barrier
	s_cbranch_vccnz .LBB0_1293
	s_setprio 1
	s_waitcnt lgkmcnt(0)
	v_mfma_f32_16x16x32_bf16 v[62:65], v[146:149], v[174:177], v[62:65]
	v_mfma_f32_16x16x32_bf16 v[58:61], v[154:157], v[174:177], v[58:61]
	v_mfma_f32_16x16x32_bf16 v[46:49], v[146:149], v[170:173], v[46:49]
	v_mfma_f32_16x16x32_bf16 v[42:45], v[154:157], v[170:173], v[42:45]
	v_mfma_f32_16x16x32_bf16 v[30:33], v[146:149], v[166:169], v[30:33]
	v_mfma_f32_16x16x32_bf16 v[26:29], v[154:157], v[166:169], v[26:29]
	v_mfma_f32_16x16x32_bf16 v[14:17], v[146:149], v[162:165], v[14:17]
	v_mfma_f32_16x16x32_bf16 v[10:13], v[154:157], v[162:165], v[10:13]
	v_mfma_f32_16x16x32_bf16 v[62:65], v[150:153], v[190:193], v[62:65]
	v_mfma_f32_16x16x32_bf16 v[58:61], v[158:161], v[190:193], v[58:61]
	v_mfma_f32_16x16x32_bf16 v[46:49], v[150:153], v[186:189], v[46:49]
	v_mfma_f32_16x16x32_bf16 v[42:45], v[158:161], v[186:189], v[42:45]
	v_mfma_f32_16x16x32_bf16 v[30:33], v[150:153], v[182:185], v[30:33]
	v_mfma_f32_16x16x32_bf16 v[26:29], v[158:161], v[182:185], v[26:29]
	v_mfma_f32_16x16x32_bf16 v[14:17], v[150:153], v[178:181], v[14:17]
	v_mfma_f32_16x16x32_bf16 v[10:13], v[158:161], v[178:181], v[10:13]
	s_setprio 0
	s_setprio 1
	v_mfma_f32_16x16x32_bf16 v[54:57], v[130:133], v[174:177], v[54:57]
	v_mfma_f32_16x16x32_bf16 v[50:53], v[138:141], v[174:177], v[50:53]
	v_mfma_f32_16x16x32_bf16 v[38:41], v[130:133], v[170:173], v[38:41]
	v_mfma_f32_16x16x32_bf16 v[34:37], v[138:141], v[170:173], v[34:37]
	v_mfma_f32_16x16x32_bf16 v[22:25], v[130:133], v[166:169], v[22:25]
	v_mfma_f32_16x16x32_bf16 v[18:21], v[138:141], v[166:169], v[18:21]
	v_mfma_f32_16x16x32_bf16 v[6:9], v[130:133], v[162:165], v[6:9]
	v_mfma_f32_16x16x32_bf16 v[2:5], v[138:141], v[162:165], v[2:5]
	v_mfma_f32_16x16x32_bf16 v[54:57], v[134:137], v[190:193], v[54:57]
	v_mfma_f32_16x16x32_bf16 v[50:53], v[142:145], v[190:193], v[50:53]
	v_mfma_f32_16x16x32_bf16 v[38:41], v[134:137], v[186:189], v[38:41]
	v_mfma_f32_16x16x32_bf16 v[34:37], v[142:145], v[186:189], v[34:37]
	v_mfma_f32_16x16x32_bf16 v[22:25], v[134:137], v[182:185], v[22:25]
	v_mfma_f32_16x16x32_bf16 v[18:21], v[142:145], v[182:185], v[18:21]
	v_mfma_f32_16x16x32_bf16 v[6:9], v[134:137], v[178:181], v[6:9]
	v_mfma_f32_16x16x32_bf16 v[2:5], v[142:145], v[178:181], v[2:5]
	s_setprio 0
.LBB0_1293:
	s_and_b64 vcc, s[34:35], s[58:59]
	v_cndmask_b32_e64 v131, v221, 0, vcc
	v_cndmask_b32_e32 v130, v220, v198, vcc
	v_lshl_add_u64 v[234:235], s[56:57], 0, v[130:131]
	s_barrier
	s_mov_b32 m0, s8
	v_lshl_add_u64 v[252:253], s[98:99], 0, v[194:195]
	global_load_lds_dwordx4 v[252:253], off
	s_mov_b32 m0, s13
	v_lshl_add_u64 v[252:253], s[98:99], 0, v[196:197]
	global_load_lds_dwordx4 v[252:253], off
	v_add_u32_e32 v130, 0x18000, v229
	v_add_u32_e32 v142, 0x1c000, v229
	ds_read_b128 v[146:149], v130
	ds_read_b128 v[150:153], v130 offset:1024
	ds_read_b128 v[154:157], v130 offset:2048
	ds_read_b128 v[158:161], v130 offset:3072
	ds_read_b128 v[130:133], v142
	ds_read_b128 v[134:137], v142 offset:1024
	ds_read_b128 v[138:141], v142 offset:2048
	ds_read_b128 v[142:145], v142 offset:3072
	s_mov_b32 m0, s14
	v_lshl_add_u64 v[236:237], v[234:235], 0, v[194:195]
	s_waitcnt lgkmcnt(0)
	ds_read_b128 v[174:177], v231 offset:32768
	ds_read_b128 v[190:193], v231 offset:33792
	ds_read_b128 v[170:173], v231 offset:34816
	ds_read_b128 v[186:189], v231 offset:35840
	ds_read_b128 v[166:169], v231 offset:36864
	ds_read_b128 v[182:185], v231 offset:37888
	ds_read_b128 v[162:165], v231 offset:38912
	ds_read_b128 v[178:181], v231 offset:39936
	global_load_lds_dwordx4 v[236:237], off
	v_lshl_add_u64 v[234:235], v[234:235], 0, v[196:197]
	s_mov_b32 m0, s15
	s_nop 0
	global_load_lds_dwordx4 v[234:235], off
	s_waitcnt vmcnt(8)
	s_waitcnt lgkmcnt(0)
	s_barrier
	s_setprio 1
	s_waitcnt lgkmcnt(0)
	v_mfma_f32_16x16x32_bf16 v[126:129], v[146:149], v[174:177], v[126:129]
	v_mfma_f32_16x16x32_bf16 v[122:125], v[154:157], v[174:177], v[122:125]
	v_mfma_f32_16x16x32_bf16 v[118:121], v[146:149], v[170:173], v[118:121]
	v_mfma_f32_16x16x32_bf16 v[110:113], v[154:157], v[170:173], v[110:113]
	v_mfma_f32_16x16x32_bf16 v[102:105], v[146:149], v[166:169], v[102:105]
	v_mfma_f32_16x16x32_bf16 v[94:97], v[154:157], v[166:169], v[94:97]
	v_mfma_f32_16x16x32_bf16 v[86:89], v[146:149], v[162:165], v[86:89]
	v_mfma_f32_16x16x32_bf16 v[78:81], v[154:157], v[162:165], v[78:81]
	v_mfma_f32_16x16x32_bf16 v[126:129], v[150:153], v[190:193], v[126:129]
	v_mfma_f32_16x16x32_bf16 v[122:125], v[158:161], v[190:193], v[122:125]
	v_mfma_f32_16x16x32_bf16 v[118:121], v[150:153], v[186:189], v[118:121]
	v_mfma_f32_16x16x32_bf16 v[110:113], v[158:161], v[186:189], v[110:113]
	v_mfma_f32_16x16x32_bf16 v[102:105], v[150:153], v[182:185], v[102:105]
	v_mfma_f32_16x16x32_bf16 v[94:97], v[158:161], v[182:185], v[94:97]
	v_mfma_f32_16x16x32_bf16 v[86:89], v[150:153], v[178:181], v[86:89]
	v_mfma_f32_16x16x32_bf16 v[78:81], v[158:161], v[178:181], v[78:81]
	s_setprio 0
	s_setprio 1
	v_mfma_f32_16x16x32_bf16 v[114:117], v[130:133], v[174:177], v[114:117]
	v_mfma_f32_16x16x32_bf16 v[106:109], v[138:141], v[174:177], v[106:109]
	v_mfma_f32_16x16x32_bf16 v[98:101], v[130:133], v[170:173], v[98:101]
	v_mfma_f32_16x16x32_bf16 v[90:93], v[138:141], v[170:173], v[90:93]
	v_mfma_f32_16x16x32_bf16 v[82:85], v[130:133], v[166:169], v[82:85]
	v_mfma_f32_16x16x32_bf16 v[74:77], v[138:141], v[166:169], v[74:77]
	v_mfma_f32_16x16x32_bf16 v[70:73], v[130:133], v[162:165], v[70:73]
	v_mfma_f32_16x16x32_bf16 v[66:69], v[138:141], v[162:165], v[66:69]
	v_mfma_f32_16x16x32_bf16 v[114:117], v[134:137], v[190:193], v[114:117]
	v_mfma_f32_16x16x32_bf16 v[106:109], v[142:145], v[190:193], v[106:109]
	v_mfma_f32_16x16x32_bf16 v[98:101], v[134:137], v[186:189], v[98:101]
	v_mfma_f32_16x16x32_bf16 v[90:93], v[142:145], v[186:189], v[90:93]
	v_mfma_f32_16x16x32_bf16 v[82:85], v[134:137], v[182:185], v[82:85]
	v_mfma_f32_16x16x32_bf16 v[74:77], v[142:145], v[182:185], v[74:77]
	v_mfma_f32_16x16x32_bf16 v[70:73], v[134:137], v[178:181], v[70:73]
	v_mfma_f32_16x16x32_bf16 v[66:69], v[142:145], v[178:181], v[66:69]
	s_setprio 0
	s_barrier
	s_and_b64 vcc, exec, s[42:43]
	s_cbranch_vccnz .LBB0_1295
	ds_read_b128 v[174:177], v231 offset:49152
	ds_read_b128 v[190:193], v231 offset:50176
	ds_read_b128 v[170:173], v231 offset:51200
	ds_read_b128 v[186:189], v231 offset:52224
	ds_read_b128 v[166:169], v231 offset:53248
	ds_read_b128 v[182:185], v231 offset:54272
	ds_read_b128 v[162:165], v231 offset:55296
	ds_read_b128 v[178:181], v231 offset:56320

.LBB0_1614:
	s_add_u32 s50, s46, s48
	s_addc_u32 s51, s47, s49
	s_add_u32 s52, s50, 0x440000
	s_addc_u32 s53, s51, 0
	s_cmp_eq_u32 s48, 0x3fc0000
	s_cselect_b64 s[56:57], -1, 0
	s_and_b64 s[50:51], s[56:57], exec
	s_cselect_b32 s51, s31, s61
	s_cselect_b32 s50, s35, s60
	s_mov_b32 m0, s10
	s_cselect_b32 s53, s19, s53
	s_cselect_b32 s52, s20, s52
	v_lshl_add_u64 v[236:237], s[50:51], 0, v[194:195]
	s_add_u32 s68, s50, 0x4000
	global_load_lds_dwordx4 v[236:237], off
	v_lshl_add_u64 v[236:237], s[50:51], 0, v[196:197]
	s_mov_b32 m0, s11
	s_addc_u32 s69, s51, 0
	global_load_lds_dwordx4 v[236:237], off
	v_lshl_add_u64 v[236:237], s[68:69], 0, v[194:195]
	s_mov_b32 m0, s12
	s_and_b64 vcc, exec, s[42:43]
	global_load_lds_dwordx4 v[236:237], off
	v_lshl_add_u64 v[236:237], s[68:69], 0, v[196:197]
	s_mov_b32 m0, s13
	s_nop 0
	global_load_lds_dwordx4 v[236:237], off
	s_mov_b64 s[98:99], s[52:53]
	s_waitcnt vmcnt(6)
	s_waitcnt lgkmcnt(0)
	s_barrier
	s_cbranch_vccnz .LBB0_1616
	s_setprio 1
	s_waitcnt lgkmcnt(0)
	v_mfma_f32_16x16x32_bf16 v[62:65], v[146:149], v[174:177], v[62:65]
	v_mfma_f32_16x16x32_bf16 v[58:61], v[154:157], v[174:177], v[58:61]
	v_mfma_f32_16x16x32_bf16 v[46:49], v[146:149], v[170:173], v[46:49]
	v_mfma_f32_16x16x32_bf16 v[42:45], v[154:157], v[170:173], v[42:45]
	v_mfma_f32_16x16x32_bf16 v[30:33], v[146:149], v[166:169], v[30:33]
	v_mfma_f32_16x16x32_bf16 v[26:29], v[154:157], v[166:169], v[26:29]
	v_mfma_f32_16x16x32_bf16 v[14:17], v[146:149], v[162:165], v[14:17]
	v_mfma_f32_16x16x32_bf16 v[10:13], v[154:157], v[162:165], v[10:13]
	v_mfma_f32_16x16x32_bf16 v[62:65], v[150:153], v[190:193], v[62:65]
	v_mfma_f32_16x16x32_bf16 v[58:61], v[158:161], v[190:193], v[58:61]
	v_mfma_f32_16x16x32_bf16 v[46:49], v[150:153], v[186:189], v[46:49]
	v_mfma_f32_16x16x32_bf16 v[42:45], v[158:161], v[186:189], v[42:45]
	v_mfma_f32_16x16x32_bf16 v[30:33], v[150:153], v[182:185], v[30:33]
	v_mfma_f32_16x16x32_bf16 v[26:29], v[158:161], v[182:185], v[26:29]
	v_mfma_f32_16x16x32_bf16 v[14:17], v[150:153], v[178:181], v[14:17]
	v_mfma_f32_16x16x32_bf16 v[10:13], v[158:161], v[178:181], v[10:13]
	s_setprio 0
	s_setprio 1
	v_mfma_f32_16x16x32_bf16 v[54:57], v[130:133], v[174:177], v[54:57]
	v_mfma_f32_16x16x32_bf16 v[50:53], v[138:141], v[174:177], v[50:53]
	v_mfma_f32_16x16x32_bf16 v[38:41], v[130:133], v[170:173], v[38:41]
	v_mfma_f32_16x16x32_bf16 v[34:37], v[138:141], v[170:173], v[34:37]
	v_mfma_f32_16x16x32_bf16 v[22:25], v[130:133], v[166:169], v[22:25]
	v_mfma_f32_16x16x32_bf16 v[18:21], v[138:141], v[166:169], v[18:21]
	v_mfma_f32_16x16x32_bf16 v[6:9], v[130:133], v[162:165], v[6:9]
	v_mfma_f32_16x16x32_bf16 v[2:5], v[138:141], v[162:165], v[2:5]
	v_mfma_f32_16x16x32_bf16 v[54:57], v[134:137], v[190:193], v[54:57]
	v_mfma_f32_16x16x32_bf16 v[50:53], v[142:145], v[190:193], v[50:53]
	v_mfma_f32_16x16x32_bf16 v[38:41], v[134:137], v[186:189], v[38:41]
	v_mfma_f32_16x16x32_bf16 v[34:37], v[142:145], v[186:189], v[34:37]
	v_mfma_f32_16x16x32_bf16 v[22:25], v[134:137], v[182:185], v[22:25]
	v_mfma_f32_16x16x32_bf16 v[18:21], v[142:145], v[182:185], v[18:21]
	v_mfma_f32_16x16x32_bf16 v[6:9], v[134:137], v[178:181], v[6:9]
	v_mfma_f32_16x16x32_bf16 v[2:5], v[142:145], v[178:181], v[2:5]
	s_setprio 0
.LBB0_1616:
	s_and_b64 vcc, s[38:39], s[56:57]
	v_cndmask_b32_e64 v131, v225, 0, vcc
	v_cndmask_b32_e32 v130, v224, v198, vcc
	v_lshl_add_u64 v[236:237], s[52:53], 0, v[130:131]
	s_barrier
	s_mov_b32 m0, s9
	v_lshl_add_u64 v[252:253], s[98:99], 0, v[194:195]
	global_load_lds_dwordx4 v[252:253], off
	s_mov_b32 m0, s14
	v_lshl_add_u64 v[252:253], s[98:99], 0, v[196:197]
	global_load_lds_dwordx4 v[252:253], off
	v_add_u32_e32 v1, 0x18000, v232
	ds_read_b128 v[146:149], v1
	ds_read_b128 v[150:153], v1 offset:1024
	ds_read_b128 v[154:157], v1 offset:2048
	ds_read_b128 v[158:161], v1 offset:3072
	v_add_u32_e32 v1, 0x1c000, v232
	ds_read_b128 v[130:133], v1
	ds_read_b128 v[134:137], v1 offset:1024
	ds_read_b128 v[138:141], v1 offset:2048
	ds_read_b128 v[142:145], v1 offset:3072
	s_mov_b32 m0, s15
	v_lshl_add_u64 v[238:239], v[236:237], 0, v[194:195]
	s_waitcnt lgkmcnt(0)
	ds_read_b128 v[174:177], v233 offset:32768
	ds_read_b128 v[190:193], v233 offset:33792
	ds_read_b128 v[170:173], v233 offset:34816
	ds_read_b128 v[186:189], v233 offset:35840
	ds_read_b128 v[166:169], v233 offset:36864
	ds_read_b128 v[182:185], v233 offset:37888
	ds_read_b128 v[162:165], v233 offset:38912
	ds_read_b128 v[178:181], v233 offset:39936
	global_load_lds_dwordx4 v[238:239], off
	v_lshl_add_u64 v[236:237], v[236:237], 0, v[196:197]
	s_mov_b32 m0, s16
	s_nop 0
	global_load_lds_dwordx4 v[236:237], off
	s_waitcnt vmcnt(8)
	s_waitcnt lgkmcnt(0)
	s_barrier
	s_setprio 1
	s_waitcnt lgkmcnt(0)
	v_mfma_f32_16x16x32_bf16 v[126:129], v[146:149], v[174:177], v[126:129]
	v_mfma_f32_16x16x32_bf16 v[122:125], v[154:157], v[174:177], v[122:125]
	v_mfma_f32_16x16x32_bf16 v[118:121], v[146:149], v[170:173], v[118:121]
	v_mfma_f32_16x16x32_bf16 v[110:113], v[154:157], v[170:173], v[110:113]
	v_mfma_f32_16x16x32_bf16 v[102:105], v[146:149], v[166:169], v[102:105]
	v_mfma_f32_16x16x32_bf16 v[94:97], v[154:157], v[166:169], v[94:97]
	v_mfma_f32_16x16x32_bf16 v[86:89], v[146:149], v[162:165], v[86:89]
	v_mfma_f32_16x16x32_bf16 v[78:81], v[154:157], v[162:165], v[78:81]
	v_mfma_f32_16x16x32_bf16 v[126:129], v[150:153], v[190:193], v[126:129]
	v_mfma_f32_16x16x32_bf16 v[122:125], v[158:161], v[190:193], v[122:125]
	v_mfma_f32_16x16x32_bf16 v[118:121], v[150:153], v[186:189], v[118:121]
	v_mfma_f32_16x16x32_bf16 v[110:113], v[158:161], v[186:189], v[110:113]
	v_mfma_f32_16x16x32_bf16 v[102:105], v[150:153], v[182:185], v[102:105]
	v_mfma_f32_16x16x32_bf16 v[94:97], v[158:161], v[182:185], v[94:97]
	v_mfma_f32_16x16x32_bf16 v[86:89], v[150:153], v[178:181], v[86:89]
	v_mfma_f32_16x16x32_bf16 v[78:81], v[158:161], v[178:181], v[78:81]
	s_setprio 0
	s_setprio 1
	v_mfma_f32_16x16x32_bf16 v[114:117], v[130:133], v[174:177], v[114:117]
	v_mfma_f32_16x16x32_bf16 v[106:109], v[138:141], v[174:177], v[106:109]
	v_mfma_f32_16x16x32_bf16 v[98:101], v[130:133], v[170:173], v[98:101]
	v_mfma_f32_16x16x32_bf16 v[90:93], v[138:141], v[170:173], v[90:93]
	v_mfma_f32_16x16x32_bf16 v[82:85], v[130:133], v[166:169], v[82:85]
	v_mfma_f32_16x16x32_bf16 v[74:77], v[138:141], v[166:169], v[74:77]
	v_mfma_f32_16x16x32_bf16 v[70:73], v[130:133], v[162:165], v[70:73]
	v_mfma_f32_16x16x32_bf16 v[66:69], v[138:141], v[162:165], v[66:69]
	v_mfma_f32_16x16x32_bf16 v[114:117], v[134:137], v[190:193], v[114:117]
	v_mfma_f32_16x16x32_bf16 v[106:109], v[142:145], v[190:193], v[106:109]
	v_mfma_f32_16x16x32_bf16 v[98:101], v[134:137], v[186:189], v[98:101]
	v_mfma_f32_16x16x32_bf16 v[90:93], v[142:145], v[186:189], v[90:93]
	v_mfma_f32_16x16x32_bf16 v[82:85], v[134:137], v[182:185], v[82:85]
	v_mfma_f32_16x16x32_bf16 v[74:77], v[142:145], v[182:185], v[74:77]
	v_mfma_f32_16x16x32_bf16 v[70:73], v[134:137], v[178:181], v[70:73]
	v_mfma_f32_16x16x32_bf16 v[66:69], v[142:145], v[178:181], v[66:69]
	s_setprio 0
	s_barrier
	s_and_b64 vcc, exec, s[42:43]
	s_cbranch_vccnz .LBB0_1618
	ds_read_b128 v[174:177], v233 offset:49152
	ds_read_b128 v[190:193], v233 offset:50176
	ds_read_b128 v[170:173], v233 offset:51200
	ds_read_b128 v[186:189], v233 offset:52224
	ds_read_b128 v[166:169], v233 offset:53248
	ds_read_b128 v[182:185], v233 offset:54272
	ds_read_b128 v[162:165], v233 offset:55296
	ds_read_b128 v[178:181], v233 offset:56320

	.amdhsa_kernel _Z8yoco_fwd4Args
		.amdhsa_group_segment_fixed_size 0
		.amdhsa_private_segment_fixed_size 0
		.amdhsa_kernarg_size 440
		.amdhsa_user_sgpr_count 2
		.amdhsa_user_sgpr_dispatch_ptr 0
		.amdhsa_user_sgpr_queue_ptr 0
		.amdhsa_user_sgpr_kernarg_segment_ptr 1
		.amdhsa_user_sgpr_dispatch_id 0
		.amdhsa_user_sgpr_kernarg_preload_length 0
		.amdhsa_user_sgpr_kernarg_preload_offset 0
		.amdhsa_user_sgpr_private_segment_size 0
		.amdhsa_uses_dynamic_stack 0
		.amdhsa_enable_private_segment 0
		.amdhsa_system_sgpr_workgroup_id_x 1
		.amdhsa_system_sgpr_workgroup_id_y 0
		.amdhsa_system_sgpr_workgroup_id_z 0
		.amdhsa_system_sgpr_workgroup_info 0
		.amdhsa_system_vgpr_workitem_id 0
		.amdhsa_next_free_vgpr 256
		.amdhsa_next_free_sgpr 100
		.amdhsa_accum_offset 256
		.amdhsa_reserve_vcc 1
		.amdhsa_float_round_mode_32 0
		.amdhsa_float_round_mode_16_64 0
		.amdhsa_float_denorm_mode_32 3
		.amdhsa_float_denorm_mode_16_64 3
		.amdhsa_dx10_clamp 1
		.amdhsa_ieee_mode 1
		.amdhsa_fp16_overflow 0
		.amdhsa_tg_split 0
		.amdhsa_exception_fp_ieee_invalid_op 0
		.amdhsa_exception_fp_denorm_src 0
		.amdhsa_exception_fp_ieee_div_zero 0
		.amdhsa_exception_fp_ieee_overflow 0
		.amdhsa_exception_fp_ieee_underflow 0
		.amdhsa_exception_fp_ieee_inexact 0
		.amdhsa_exception_int_div_zero 0
	.end_amdhsa_kernel

amdhsa.kernels:
  - .agpr_count:     0
    .args:
      - .offset:         0
        .size:           184
        .value_kind:     by_value
      - .offset:         184
        .size:           4
        .value_kind:     hidden_block_count_x
      - .offset:         188
        .size:           4
        .value_kind:     hidden_block_count_y
      - .offset:         192
        .size:           4
        .value_kind:     hidden_block_count_z
      - .offset:         196
        .size:           2
        .value_kind:     hidden_group_size_x
      - .offset:         198
        .size:           2
        .value_kind:     hidden_group_size_y
      - .offset:         200
        .size:           2
        .value_kind:     hidden_group_size_z
      - .offset:         202
        .size:           2
        .value_kind:     hidden_remainder_x
      - .offset:         204
        .size:           2
        .value_kind:     hidden_remainder_y
      - .offset:         206
        .size:           2
        .value_kind:     hidden_remainder_z
      - .offset:         224
        .size:           8
        .value_kind:     hidden_global_offset_x
      - .offset:         232
        .size:           8
        .value_kind:     hidden_global_offset_y
      - .offset:         240
        .size:           8
        .value_kind:     hidden_global_offset_z
      - .offset:         248
        .size:           2
        .value_kind:     hidden_grid_dims
      - .offset:         304
        .size:           4
        .value_kind:     hidden_dynamic_lds_size
    .group_segment_fixed_size: 0
    .kernarg_segment_align: 8
    .kernarg_segment_size: 440
    .language:       OpenCL C
    .language_version:
      - 2
      - 0
    .max_flat_workgroup_size: 512
    .name:           _Z8yoco_fwd4Args
    .private_segment_fixed_size: 0
    .sgpr_count:     106
    .sgpr_spill_count: 153
    .symbol:         _Z8yoco_fwd4Args.kd
    .uniform_work_group_size: 1
    .uses_dynamic_stack: false
    .vgpr_count:     256
    .vgpr_spill_count: 0
    .wavefront_size: 64
